# one static s_setprio 1 for waves 0-3 at kernel entry (the other half; flip-free K-loops)
# speedup vs baseline: 1.0008x; 1.0008x over previous
; #define LAS __attribute__((address_space(3)))
; __device__ __forceinline__ XcdBarrier xcd_barrier_post(unsigned* bar, volatile LAS unsigned* st) {
;     XcdBarrier b; b.bar = bar; b.x = xb_xcc_id(); b.st = st;
;     if (threadIdx.x == 0) (void)xb_add(&bar[XB_XCNT(b.x)], 1u);
;     return b;
; }
; __device__ __forceinline__ void xcd_barrier_complete(unsigned* bar, unsigned x, unsigned& nloc, unsigned& nx) {
;     const unsigned G = gridDim.x * gridDim.y * gridDim.z;
;     unsigned sum, cnt, mine, sp = 0u;
;     for (;;) {
;         sum = 0u; cnt = 0u; mine = 0u;
; #pragma unroll
;         for (unsigned j = 0; j < 16; ++j) { const unsigned c = xb_ld(&bar[XB_XCNT(j)]); sum += c; cnt += (c > 0u) ? 1u : 0u; mine = (j == x) ? c : mine; }
;         if (sum == G) break;
;         __builtin_amdgcn_s_sleep(1);
;         if ((++sp & 255u) == 0u) { if (xb_ld(&bar[XB_TMO])) break; if (sp > XB_SPIN_CAP) { atomicAdd(&bar[XB_TMO], 1u); break; } }
;     }
;     nloc = mine > 0u ? mine : 1u; nx = cnt > 0u ? cnt : 1u;
; }
; __device__ __forceinline__ void xcd_barrier(const XcdBarrier& b) {
;     asm volatile("s_waitcnt vmcnt(0)" ::: "memory");
;     __syncthreads();
;     if (threadIdx.x == 0) {
;         unsigned* bar = b.bar;
;         __builtin_amdgcn_s_waitcnt(0);
;         unsigned nloc = b.st[0], nx = b.st[1];
;         if (nloc == 0u) { xcd_barrier_complete(bar, b.x, nloc, nx); b.st[0] = nloc; b.st[1] = nx; }
;         const unsigned old = xb_add(&bar[XB_XSUB(b.x)], 1u);
;         const unsigned gen = old / nloc;
;         if (old + 1u == (gen + 1u) * nloc) {
;             __builtin_amdgcn_fence(__ATOMIC_RELEASE, "agent");
;             asm volatile("s_waitcnt vmcnt(0)" ::: "memory");
;             const unsigned og = xb_add(&bar[XB_TOP], 1u);
;             const unsigned tg = og / nx;
;             if (og + 1u == (tg + 1u) * nx) xb_add(&bar[XB_TOPGEN], 1u);
;             else XB_SPIN(xb_ld(&bar[XB_TOPGEN]) == tg, bar);
;             __builtin_amdgcn_fence(__ATOMIC_ACQUIRE, "agent");
;             xb_add(&bar[XB_XGEN(b.x)], 1u);
; __device__ __forceinline__ void norm_phase(const float* xl, const float* xc, bf16_t* HN, const float* gain, const float* mods_l, int sidx, int nrows, int lane, int gw, int NGW,
;                                            float* ctxr_rw, const float* part, int npart, const float* pgate) {
;     const bool blocked = (ML % NGW) == 0;
.LBB0_5:
	s_or_b64 exec, exec, s[2:3]
	s_cmp_ge_i32 s70, s71
	s_cbranch_scc1 .LBB0_601
	v_readlane_b32 s8, v253, 0
	s_lshl_b32 s5, s8, 9
	s_cmpk_lg_i32 s8, 0x100
	s_cselect_b64 s[2:3], -1, 0
	v_readlane_b32 s9, v253, 1
	v_writelane_b32 v253, s2, 8
	s_lshl_b32 s15, s8, 3
	v_lshrrev_b32_e32 v2, 20, v0
	v_writelane_b32 v253, s3, 9
	s_ashr_i32 s2, s8, 31
	v_writelane_b32 v253, s2, 10
	s_add_i32 s3, s15, 0x7fff
	s_add_i32 s2, s15, 0x7ff
	s_add_u32 s10, s68, 0x800200
	s_addc_u32 s11, s69, 0
	s_add_u32 s46, s68, 0x800400
	s_addc_u32 s47, s69, 0
	s_add_u32 s48, s68, 0x800500
	s_addc_u32 s49, s69, 0
	s_add_u32 s50, s68, 0x800600
	v_writelane_b32 v253, s10, 11
	s_addc_u32 s51, s69, 0
	v_lshrrev_b32_e32 v0, 10, v0
	v_writelane_b32 v253, s11, 12
	s_add_u32 s10, s68, 0x800700
	s_addc_u32 s11, s69, 0
	v_writelane_b32 v253, s10, 13
	v_or_b32_e32 v0, v0, v2
	v_mov_b32_e32 v49, 0
	v_writelane_b32 v253, s11, 14
	s_add_u32 s10, s68, 0x800800
	s_addc_u32 s11, s69, 0
	v_writelane_b32 v253, s10, 15
	v_mov_b32_e32 v221, 0x3ecc95a3
	v_mov_b32_e32 v223, 0x358637bd
	v_writelane_b32 v253, s11, 16
	s_add_u32 s10, s68, 0x800900
	s_addc_u32 s11, s69, 0
	v_writelane_b32 v253, s10, 17
	v_mov_b32_e32 v230, 1
	v_mov_b32_e32 v174, 0x3f317218
	v_writelane_b32 v253, s11, 18
	s_add_u32 s10, s68, 0x800a00
	s_addc_u32 s11, s69, 0
	v_writelane_b32 v253, s10, 19
	v_mov_b32_e32 v249, 0x7f800000
	v_mov_b32_e32 v250, 0x7fc00000
	v_writelane_b32 v253, s11, 20
	s_add_u32 s10, s68, 0x800b00
	s_addc_u32 s11, s69, 0
	v_writelane_b32 v253, s10, 21
	v_mov_b32_e32 v251, 0xff800000
	v_mov_b32_e32 v231, 0xff
	v_writelane_b32 v253, s11, 22
	s_add_u32 s10, s68, 0x800c00
	s_addc_u32 s11, s69, 0
	v_writelane_b32 v253, s10, 23
	v_mov_b32_e32 v232, 0xfff
	v_mov_b32_e32 v233, 0xf149f2ca
	v_writelane_b32 v253, s11, 24
	s_add_u32 s10, s68, 0x800d00
	s_addc_u32 s11, s69, 0
	v_writelane_b32 v253, s10, 25
	v_mov_b32_e32 v252, 0x14400
	v_mov_b32_e32 v244, 0x19e00
	v_writelane_b32 v253, s11, 26
	s_add_u32 s10, s68, 0x800e00
	s_addc_u32 s11, s69, 0
	v_writelane_b32 v253, s10, 27
	v_mov_b32_e32 v245, 0x1a700
	v_mov_b32_e32 v246, 0x1b900
	v_writelane_b32 v253, s11, 28
	s_add_u32 s10, s68, 0x800f00
	s_addc_u32 s11, s69, 0
	v_writelane_b32 v253, s10, 29
	v_mov_b32_e32 v247, 0x1c200
	v_mov_b32_e32 v248, 0x1cb00
	v_writelane_b32 v253, s11, 30
	s_add_u32 s10, s68, 0x801000
	s_addc_u32 s11, s69, 0
	v_writelane_b32 v253, s10, 31
	s_mov_b32 s58, 0x48000
	s_mov_b32 s57, 0
	v_writelane_b32 v253, s11, 32
	s_add_u32 s10, s68, 0x801100
	s_addc_u32 s11, s69, 0
	v_writelane_b32 v253, s10, 33
	s_mov_b32 s14, 0xbfb8aa3b
	s_nop 0
	v_writelane_b32 v253, s11, 34
	s_add_u32 s10, s68, 0x801200
	s_addc_u32 s11, s69, 0
	v_writelane_b32 v253, s10, 35
	s_nop 1
	v_writelane_b32 v253, s11, 36
	s_add_u32 s10, s68, 0x801300
	s_addc_u32 s11, s69, 0
	v_writelane_b32 v253, s10, 37
	s_cmp_eq_u32 s6, 15
	s_nop 0
	v_writelane_b32 v253, s11, 38
	s_cselect_b64 s[10:11], -1, 0
	v_writelane_b32 v253, s10, 39
	s_cmp_eq_u32 s6, 14
	s_nop 0
	v_writelane_b32 v253, s11, 40
	s_cselect_b64 s[10:11], -1, 0
	v_writelane_b32 v253, s10, 41
	s_cmp_eq_u32 s6, 13
	s_nop 0
	v_writelane_b32 v253, s11, 42
	s_cselect_b64 s[10:11], -1, 0
	v_writelane_b32 v253, s10, 43
	s_cmp_eq_u32 s6, 12
	s_nop 0
	v_writelane_b32 v253, s11, 44
	s_cselect_b64 s[10:11], -1, 0
	v_writelane_b32 v253, s10, 45
	s_cmp_eq_u32 s6, 11
	s_nop 0
	v_writelane_b32 v253, s11, 46
	s_cselect_b64 s[10:11], -1, 0
	v_writelane_b32 v253, s10, 47
	s_cmp_eq_u32 s6, 10
	s_nop 0
	v_writelane_b32 v253, s11, 48
	s_cselect_b64 s[10:11], -1, 0
	v_writelane_b32 v253, s10, 49
	s_cmp_eq_u32 s6, 9
	s_nop 0
	v_writelane_b32 v253, s11, 50
	s_cselect_b64 s[10:11], -1, 0
	v_writelane_b32 v253, s10, 51
	s_cmp_eq_u32 s6, 8
	s_nop 0
	v_writelane_b32 v253, s11, 52
	s_cselect_b64 s[10:11], -1, 0
	v_writelane_b32 v253, s10, 53
	s_cmp_eq_u32 s6, 7
	s_nop 0
	v_writelane_b32 v253, s11, 54
	s_cselect_b64 s[10:11], -1, 0
	v_writelane_b32 v253, s10, 55
	s_cmp_eq_u32 s6, 6
	s_nop 0
	v_writelane_b32 v253, s11, 56
	s_cselect_b64 s[10:11], -1, 0
	v_writelane_b32 v253, s10, 57
	s_cmp_eq_u32 s6, 5
	s_nop 0
	v_writelane_b32 v253, s11, 58
	s_cselect_b64 s[10:11], -1, 0
	v_writelane_b32 v253, s10, 59
	s_cmp_eq_u32 s6, 4
	s_nop 0
	v_writelane_b32 v253, s11, 60
	s_cselect_b64 s[10:11], -1, 0
	v_writelane_b32 v253, s10, 61
	s_cmp_eq_u32 s6, 3
	s_nop 0
	v_writelane_b32 v253, s11, 62
	s_cselect_b64 s[10:11], -1, 0
	v_writelane_b32 v253, s10, 63
	s_cmp_eq_u32 s6, 2
	s_nop 0
	v_writelane_b32 v254, s11, 0
	s_cselect_b64 s[10:11], -1, 0
	v_writelane_b32 v254, s10, 1
	s_cmp_eq_u32 s6, 1
	s_nop 0
	v_writelane_b32 v254, s11, 2
	s_cselect_b64 s[10:11], -1, 0
	v_writelane_b32 v254, s10, 3
	s_cmp_eq_u32 s6, 0
	s_nop 0
	v_writelane_b32 v254, s11, 4
	s_cselect_b64 s[10:11], -1, 0
	s_lshl_b32 s4, s6, 8
	s_add_u32 s0, s0, s4
	s_addc_u32 s1, s1, 0
	v_writelane_b32 v254, s10, 5
	s_add_u32 s6, s0, 0x1400
	s_addc_u32 s7, s1, 0
	v_writelane_b32 v254, s11, 6
	v_writelane_b32 v254, s6, 7
	s_add_u32 s0, s0, 0x2400
	s_addc_u32 s1, s1, 0
	v_writelane_b32 v254, s7, 8
	v_writelane_b32 v254, s0, 9
	s_nop 1
	v_writelane_b32 v254, s1, 10
	s_add_u32 s0, s68, 0x803400
	s_addc_u32 s1, s69, 0
	v_writelane_b32 v254, s0, 11
	s_nop 1
	v_writelane_b32 v254, s1, 12
	s_add_u32 s0, s68, 0x803500
	s_addc_u32 s1, s69, 0
	s_abs_i32 s4, s8
	v_cvt_f32_u32_e32 v1, s4
	v_writelane_b32 v254, s0, 13
	s_mov_b32 s69, s5
	s_movk_i32 s68, 0x23f
	v_rcp_iflag_f32_e32 v1, v1
	v_writelane_b32 v254, s1, 14
	s_sub_i32 s0, 0, s4
	v_mul_f32_e32 v1, 0x4f7ffffe, v1
	v_cvt_u32_f32_e32 v1, v1
	s_nop 0
	v_readfirstlane_b32 s1, v1
	s_mul_i32 s0, s0, s1
	s_mul_hi_u32 s0, s1, s0
	s_add_i32 s0, s1, s0
	v_writelane_b32 v254, s0, 15
	s_lshr_b32 s0, s0, 26
	s_mul_i32 s0, s0, s4
	s_sub_i32 s0, 64, s0
	s_sub_i32 s1, s0, s4
	s_cmp_ge_u32 s0, s4
	s_cselect_b32 s0, s1, s0
	s_sub_i32 s1, s0, s4
	s_cmp_ge_u32 s0, s4
	s_cselect_b32 s0, s1, s0
	s_abs_i32 s33, s15
	v_cvt_f32_u32_e32 v1, s33
	v_writelane_b32 v254, s4, 16
	v_readlane_b32 s4, v253, 2
	v_readlane_b32 s5, v253, 3
	v_rcp_iflag_f32_e32 v1, v1
	s_load_dword s1, s[4:5], 0xf0
	v_writelane_b32 v254, s0, 17
	s_mul_i32 s0, s9, s8
	v_mul_f32_e32 v1, 0x4f7ffffe, v1
	v_cvt_u32_f32_e32 v1, v1
	s_waitcnt lgkmcnt(0)
; #define LAS __attribute__((address_space(3)))
; __device__ __forceinline__ void norm_phase(const float* xl, const float* xc, bf16_t* HN, const float* gain, const float* mods_l, int sidx, int nrows, int lane, int gw, int NGW,
;                                            float* ctxr_rw, const float* part, int npart, const float* pgate) {
;     const bool blocked = (ML % NGW) == 0;
;     const int rpw = blocked ? ML / NGW : (ML + NGW - 1) / NGW;
;     const int nctx = nrows > ML ? (nrows - ML + NGW - 1) / NGW : 0;
; __global__ void __launch_bounds__(512, 2) fwd_kernel(Args a) {
;     ...
;     volatile LAS unsigned* bst = (volatile LAS unsigned*)(lds + 131072 + 64);
;     if (threadIdx.x < 4) bst[threadIdx.x] = 0u;
;     __syncthreads();
;     const XcdBarrier bar = xcd_barrier_post((unsigned*)(a.ws + WS_BAR), bst);
	s_mul_i32 s55, s0, s1
	s_movk_i32 s0, 0x3ff
	v_and_or_b32 v0, v0, s0, v220
	s_sub_i32 s0, 0, s33
	v_readfirstlane_b32 s1, v1
	s_mul_i32 s0, s0, s1
	s_mul_hi_u32 s0, s1, s0
	s_add_i32 s52, s1, s0
	s_lshr_b32 s0, s52, 17
	s_mul_i32 s0, s0, s33
	s_sub_i32 s0, 0x8000, s0
	s_ashr_i32 s4, s15, 31
	s_sub_i32 s1, s0, s33
	s_cmp_ge_u32 s0, s33
	s_cselect_b32 s0, s1, s0
	s_sub_i32 s1, s0, s33
	s_cmp_ge_u32 s0, s33
	s_cselect_b32 s0, s1, s0
	s_cmp_lg_u32 s0, 0
	s_cselect_b64 s[0:1], -1, 0
	v_writelane_b32 v254, s0, 18
	v_mbcnt_lo_u32_b32 v1, -1, 0
	s_nop 0
	v_writelane_b32 v254, s1, 19
	s_and_b64 s[0:1], s[0:1], exec
	s_cselect_b32 s0, s3, 0x8000
	s_abs_i32 s1, s0
	s_mul_hi_u32 s3, s1, s52
	s_mul_i32 s5, s3, s33
	s_sub_i32 s1, s1, s5
	s_ashr_i32 s0, s0, 31
	s_xor_b32 s0, s0, s4
	s_add_i32 s5, s3, 1
	s_sub_i32 s6, s1, s33
	s_cmp_ge_u32 s1, s33
	s_cselect_b32 s3, s5, s3
	s_cselect_b32 s1, s6, s1
	s_add_i32 s5, s3, 1
	s_cmp_ge_u32 s1, s33
	s_cselect_b32 s1, s5, s3
	s_xor_b32 s1, s1, s0
	s_sub_i32 s0, s1, s0
	s_sub_i32 s1, 0xfffff801, s15
	s_max_i32 s1, s2, s1
	v_writelane_b32 v254, s0, 20
	s_ashr_i32 s0, s2, 31
	s_mul_hi_u32 s2, s1, s52
	s_mul_i32 s3, s2, s33
	s_sub_i32 s1, s1, s3
	s_xor_b32 s0, s0, s4
	s_add_i32 s3, s2, 1
	s_sub_i32 s4, s1, s33
	s_cmp_ge_u32 s1, s33
	s_cselect_b32 s2, s3, s2
	s_cselect_b32 s1, s4, s1
	s_add_i32 s3, s2, 1
	s_cmp_ge_u32 s1, s33
	s_cselect_b32 s1, s3, s2
	s_xor_b32 s1, s1, s0
	s_sub_i32 s0, s1, s0
	v_writelane_b32 v254, s0, 21
	s_lshl_b32 s0, s8, 1
	v_writelane_b32 v254, s0, 22
	s_lshl_b32 s0, s8, 7
	v_writelane_b32 v254, s0, 23
	s_lshl_b32 s0, s8, 5
	v_writelane_b32 v254, s0, 24
	s_add_i32 s0, 0, 0x20400
	v_writelane_b32 v254, s0, 25
	s_add_i32 s0, 0, 0x11000
	v_writelane_b32 v254, s0, 26
	s_add_i32 s0, 0, 0x20040
	v_writelane_b32 v254, s0, 27
	s_add_i32 s0, 0, 0x20044
	v_writelane_b32 v254, s0, 28
	v_cmp_eq_u32_e64 s[0:1], 0, v0
	v_mbcnt_hi_u32_b32 v222, -1, v1
	v_and_b32_e32 v1, 64, v222
	v_writelane_b32 v254, s0, 29
	v_xor_b32_e32 v226, 32, v222
	v_add_u32_e32 v227, 64, v1
	v_writelane_b32 v254, s1, 30
	v_writelane_b32 v254, s54, 31
	v_writelane_b32 v254, s69, 32
	v_writelane_b32 v254, s46, 33
	s_movk_i32 s4, 0x6000
	s_movk_i32 s5, 0x90
	v_writelane_b32 v254, s47, 34
	v_writelane_b32 v254, s48, 35
	s_mov_b64 s[0:1], 0x80
	s_nop 0
	v_writelane_b32 v254, s49, 36
	v_writelane_b32 v254, s50, 37
	s_nop 1
	v_writelane_b32 v254, s51, 38
	v_writelane_b32 v254, s55, 39
	v_writelane_b32 v254, s52, 40
	v_readfirstlane_b32 s98, v220
	s_cmpk_ge_u32 s98, 0x100
	s_cbranch_scc1 .Lprio_done
	s_setprio 1
